# latent Hyena K loop: shared B fragments fetched HBM->LDS directly (LDS-DMA, m0 lane-linear image) instead of VGPR staging + ds_write
# baseline (speedup 1.0000x reference)
; DI void hyena_item_lat(const Params& p, int l, int it) {
;     ...
;   const u16* ub = UT + ((size_t)(c * 16 + l16)) * TPB + posoff + kg * 8;
;   const u16* rsel = (l16 & 1) ? (R1 - 1) : R0;
;   const int nb = L - (tt0 + l16) + kg * 8;
;   union AF { u32 u[4]; bf16x8 v; };
;   AF a[8];
;     ...
; #pragma unroll
;   for (int i = 2; i < 8; ++i) HY_LOADA(a[i], nb - 16 * i)
; #pragma unroll 1
;   for (int sb = 0; sb < L; sb += 128) {
; #pragma unroll
;     for (int u = 0; u < 4; ++u) {
;       const int s0 = sb + 32 * u;
;       HY_LOADA(a[(0 - 2 * u) & 7], nb + s0)
;       HY_LOADA(a[(1 - 2 * u) & 7], nb - 16 + s0)
;       const bf16x8 bfrag = *(const bf16x8*)(ub + s0);
; #pragma unroll
;       for (int i = 0; i < 8; ++i) acc[i] = __builtin_amdgcn_mfma_f32_16x16x32_bf16(a[(i - 2 * u) & 7].v, bfrag, acc[i], 0, 0, 0);
;     }
;   }
.LBB0_1137:
	s_andn2_b64 vcc, exec, s[34:35]
	s_cbranch_vccnz .LBB0_1141
	s_ashr_i32 s34, s13, 2
	v_mov_b32_e32 v0, v218
	v_mov_b32_e32 v1, v218
	s_add_i32 s36, s34, s42
	s_lshl_b32 s13, s13, 9
	s_ashr_i32 s37, s36, 31
	s_mul_i32 s38, s36, 0x4040
	v_readlane_b32 s16, v254, 47
	v_lshlrev_b32_e32 v1, 1, v1
	s_mul_hi_i32 s35, s36, 0x4040
	v_readlane_b32 s17, v254, 48
	s_add_u32 s38, s16, s38
	v_and_b32_e32 v1, 0xffffff80, v1
	s_addc_u32 s39, s17, s35
	s_and_b32 s13, s13, 0x600
	v_add_u32_e32 v63, s13, v1
	v_and_b32_e32 v62, 15, v0
	v_bfe_u32 v64, v0, 4, 2
	v_bfe_i32 v0, v0, 0, 1
	v_lshlrev_b32_e32 v1, 3, v64
	v_and_b32_e32 v172, 0x201e, v0
	v_or_b32_e32 v0, v63, v62
	v_sub_u32_e32 v58, v1, v0
	v_lshl_add_u64 v[56:57], s[38:39], 0, v[172:173]
	v_ashrrev_i32_e32 v59, 31, v58
	v_lshl_add_u64 v[0:1], v[58:59], 1, v[56:57]
	global_load_dwordx4 v[40:43], v[0:1], off offset:4032
	global_load_dwordx4 v[44:47], v[0:1], off offset:4000
	global_load_dwordx4 v[32:35], v[0:1], off offset:3968
	global_load_dwordx4 v[36:39], v[0:1], off offset:3936
	global_load_dwordx4 v[48:51], v[0:1], off offset:3904
	global_load_dwordx4 v[52:55], v[0:1], off offset:3872
	s_lshl_b32 s35, s34, 4
	v_or_b32_e32 v59, s35, v62
	v_mad_i64_i32 v[0:1], s[38:39], v59, s9, 0
	v_readlane_b32 s16, v255, 56
	v_lshl_or_b32 v0, v64, 4, v0
	v_readlane_b32 s17, v255, 57
	v_mov_b32_e32 v28, 0
	s_mov_b64 s[46:47], s[20:21]
	s_movk_i32 s13, 0xff80
	v_lshl_add_u64 v[60:61], s[16:17], 0, v[0:1]
	v_mov_b32_e32 v29, v28
	v_mov_b32_e32 v30, v28
	v_mov_b32_e32 v31, v28
	v_mov_b32_e32 v24, v28
	v_mov_b32_e32 v25, v28
	v_mov_b32_e32 v26, v28
	v_mov_b32_e32 v27, v28
	v_mov_b32_e32 v20, v28
	v_mov_b32_e32 v21, v28
	v_mov_b32_e32 v22, v28
	v_mov_b32_e32 v23, v28
	v_mov_b32_e32 v16, v28
	v_mov_b32_e32 v17, v28
	v_mov_b32_e32 v18, v28
	v_mov_b32_e32 v19, v28
	v_mov_b32_e32 v12, v28
	v_mov_b32_e32 v13, v28
	v_mov_b32_e32 v14, v28
	v_mov_b32_e32 v15, v28
	v_mov_b32_e32 v8, v28
	v_mov_b32_e32 v9, v28
	v_mov_b32_e32 v10, v28
	v_mov_b32_e32 v11, v28
	v_mov_b32_e32 v4, v28
	v_mov_b32_e32 v5, v28
	v_mov_b32_e32 v6, v28
	v_mov_b32_e32 v7, v28
	v_mov_b32_e32 v0, v28
	v_mov_b32_e32 v1, v28
	v_mov_b32_e32 v2, v28
	v_mov_b32_e32 v3, v28
	v_and_b32_e32 v92, 0xc0, v218
	v_add_u32_e32 v92, 0xffffff40, v92
	v_lshrrev_b32_e32 v94, 6, v218
	v_ashrrev_i32_e32 v93, 31, v92
	v_lshlrev_b32_e32 v94, 10, v94
	v_and_b32_e32 v95, 63, v218
	v_lshl_add_u64 v[90:91], v[92:93], 0, v[60:61]
	v_readfirstlane_b32 s32, v94
	v_lshlrev_b32_e32 v95, 4, v95
	s_nop 0
	s_mov_b32 m0, s32
	s_mov_b64 s[38:39], 0x100
	global_load_lds_dwordx4 v[90:91], off
	v_lshl_add_u64 v[90:91], v[90:91], 0, s[38:39]
.LBB0_1139:
	s_waitcnt vmcnt(0)
	s_barrier
	s_xor_b32 s32, s32, 0x1000
	ds_read_b128 v[66:69], v95
	ds_read_b128 v[70:73], v95 offset:1024
	ds_read_b128 v[86:89], v95 offset:2048
	ds_read_b128 v[74:77], v95 offset:3072
	v_xor_b32_e32 v95, 0x1000, v95
	s_mov_b64 s[38:39], 0x100
	s_waitcnt lgkmcnt(0)
	v_mfma_f32_16x16x32_bf16 v[4:7], v[48:51], v[66:69], v[4:7]
	v_add_u32_e32 v49, s13, v58
	v_add_u32_e32 v48, 0x880, v49
	v_add_u32_e32 v50, 0x870, v49
	v_mfma_f32_16x16x32_bf16 v[0:3], v[52:55], v[66:69], v[0:3]
	v_ashrrev_i32_e32 v49, 31, v48
	v_ashrrev_i32_e32 v51, 31, v50
	v_lshl_add_u64 v[78:79], v[48:49], 1, v[56:57]
	v_lshl_add_u64 v[80:81], v[50:51], 1, v[56:57]
	v_mfma_f32_16x16x32_bf16 v[12:15], v[32:35], v[66:69], v[12:15]
	global_load_dwordx4 v[48:51], v[78:79], off offset:64
	global_load_dwordx4 v[52:55], v[80:81], off offset:64
	s_addk_i32 s13, 0x80
	v_mfma_f32_16x16x32_bf16 v[8:11], v[36:39], v[66:69], v[8:11]
	s_cmpk_lt_u32 s13, 0x780
	v_mfma_f32_16x16x32_bf16 v[4:7], v[32:35], v[70:73], v[4:7]
	global_load_dwordx4 v[32:35], v[78:79], off
	v_mfma_f32_16x16x32_bf16 v[0:3], v[36:39], v[70:73], v[0:3]
	global_load_dwordx4 v[36:39], v[80:81], off
	v_mfma_f32_16x16x32_bf16 v[20:23], v[40:43], v[66:69], v[20:23]
	v_mfma_f32_16x16x32_bf16 v[16:19], v[44:47], v[66:69], v[16:19]
	s_waitcnt vmcnt(1)
	v_mfma_f32_16x16x32_bf16 v[28:31], v[32:35], v[66:69], v[28:31]
	s_waitcnt vmcnt(0)
	v_mfma_f32_16x16x32_bf16 v[24:27], v[36:39], v[66:69], v[24:27]
	s_mov_b32 m0, s32
	s_nop 0
	global_load_lds_dwordx4 v[90:91], off
	v_lshl_add_u64 v[90:91], v[90:91], 0, s[38:39]
	v_lshl_add_u64 v[60:61], v[60:61], 0, s[38:39]
	v_mfma_f32_16x16x32_bf16 v[12:15], v[40:43], v[70:73], v[12:15]
	v_mfma_f32_16x16x32_bf16 v[8:11], v[44:47], v[70:73], v[8:11]
	v_mfma_f32_16x16x32_bf16 v[20:23], v[32:35], v[70:73], v[20:23]
	v_mfma_f32_16x16x32_bf16 v[16:19], v[36:39], v[70:73], v[16:19]
	v_mfma_f32_16x16x32_bf16 v[28:31], v[48:51], v[70:73], v[28:31]
	v_mfma_f32_16x16x32_bf16 v[24:27], v[52:55], v[70:73], v[24:27]
	v_mfma_f32_16x16x32_bf16 v[4:7], v[40:43], v[86:89], v[4:7]
	global_load_dwordx4 v[40:43], v[78:79], off offset:192
	v_mfma_f32_16x16x32_bf16 v[0:3], v[44:47], v[86:89], v[0:3]
	global_load_dwordx4 v[44:47], v[80:81], off offset:192
	v_mfma_f32_16x16x32_bf16 v[12:15], v[32:35], v[86:89], v[12:15]
	v_mfma_f32_16x16x32_bf16 v[8:11], v[36:39], v[86:89], v[8:11]
	v_mfma_f32_16x16x32_bf16 v[4:7], v[32:35], v[74:77], v[4:7]
	global_load_dwordx4 v[32:35], v[78:79], off offset:128
	v_mfma_f32_16x16x32_bf16 v[0:3], v[36:39], v[74:77], v[0:3]
	global_load_dwordx4 v[36:39], v[80:81], off offset:128
	v_mfma_f32_16x16x32_bf16 v[20:23], v[48:51], v[86:89], v[20:23]
	v_mfma_f32_16x16x32_bf16 v[16:19], v[52:55], v[86:89], v[16:19]
	v_mfma_f32_16x16x32_bf16 v[12:15], v[48:51], v[74:77], v[12:15]
	v_mfma_f32_16x16x32_bf16 v[8:11], v[52:55], v[74:77], v[8:11]
	s_waitcnt vmcnt(1)
	v_mfma_f32_16x16x32_bf16 v[28:31], v[32:35], v[86:89], v[28:31]
	s_waitcnt vmcnt(0)
	v_mfma_f32_16x16x32_bf16 v[24:27], v[36:39], v[86:89], v[24:27]
	v_mfma_f32_16x16x32_bf16 v[20:23], v[32:35], v[74:77], v[20:23]
	v_mfma_f32_16x16x32_bf16 v[16:19], v[36:39], v[74:77], v[16:19]
	v_mfma_f32_16x16x32_bf16 v[28:31], v[40:43], v[74:77], v[28:31]
	v_mfma_f32_16x16x32_bf16 v[24:27], v[44:47], v[74:77], v[24:27]
	s_cbranch_scc1 .LBB0_1139
; DI float bf2f(u16 v) { return __uint_as_float(((u32)v) << 16); }
; DI void hyena_item_lat(const Params& p, int l, int it) {
;     ...
;   float ssq = 0.f;
;   for (int t = 0; t < 32; ++t) ssq += WSP(const float, OFF_PART)[(size_t)(f * 32 + t) * 256 + c];
;   const float scale = rsqrtf(ssq + EPSF);
;   const float bias = p.in[I_HYBIAS][l * 256 + c];
;   const u16* X1C = WSP(const u16, OFF_X1C);
;   u16* YM = WSP(u16, OFF_ACT);
;   const int b = l16;
; #pragma unroll
;   for (int i = 0; i < 8; ++i)
; #pragma unroll
;     for (int r = 0; r < 4; ++r) {
;       const int t = tt0 + 16 * i + kg * 4 + r;
;       const size_t row = (size_t)b * TPB + posoff + t;
;       const float uu = bf2f(UT[((size_t)(c * 16 + b)) * TPB + posoff + t]);
	s_waitcnt vmcnt(0)
	v_mov_b64_e32 v[32:33], s[96:97]
	v_mad_i64_i32 v[32:33], s[38:39], v59, s9, v[32:33]
	s_mov_b64 s[38:39], 0x15600200
	s_ashr_i32 s35, s34, 31
	v_lshl_add_u64 v[32:33], v[32:33], 0, s[38:39]
	s_lshl_b64 s[38:39], s[34:35], 2
	s_add_u32 s38, s43, s38
	s_addc_u32 s39, s44, s39
	global_load_dword v38, v173, s[38:39]
	global_load_dword v39, v173, s[38:39] offset:1024
	global_load_dword v40, v173, s[38:39] offset:2048
	global_load_dword v41, v173, s[38:39] offset:3072
	v_mov_b32_e32 v92, 0x1000
	global_load_dword v42, v92, s[38:39]
	global_load_dword v43, v92, s[38:39] offset:1024
	global_load_dword v44, v92, s[38:39] offset:2048
	global_load_dword v45, v92, s[38:39] offset:3072
	v_mov_b32_e32 v92, 0x2000
	global_load_dword v46, v92, s[38:39]
	global_load_dword v47, v92, s[38:39] offset:1024
	global_load_dword v48, v92, s[38:39] offset:2048
	global_load_dword v49, v92, s[38:39] offset:3072
	v_mov_b32_e32 v92, 0x3000
	global_load_dword v50, v92, s[38:39]
	global_load_dword v51, v92, s[38:39] offset:1024
	global_load_dword v52, v92, s[38:39] offset:2048
	global_load_dword v53, v92, s[38:39] offset:3072
	v_mov_b32_e32 v92, 0x4000
	global_load_dword v54, v92, s[38:39]
	global_load_dword v55, v92, s[38:39] offset:1024
	global_load_dword v56, v92, s[38:39] offset:2048
	global_load_dword v57, v92, s[38:39] offset:3072
	v_mov_b32_e32 v92, 0x5000
	global_load_dword v58, v92, s[38:39]
	global_load_dword v65, v92, s[38:39] offset:1024
	global_load_dword v66, v92, s[38:39] offset:2048
	global_load_dword v67, v92, s[38:39] offset:3072
	v_mov_b32_e32 v92, 0x6000
	global_load_dword v68, v92, s[38:39]
	global_load_dword v69, v92, s[38:39] offset:1024
	global_load_dword v70, v92, s[38:39] offset:2048
	global_load_dword v71, v92, s[38:39] offset:3072
	v_mov_b32_e32 v92, 0x7000
	global_load_dword v72, v92, s[38:39]
	global_load_dword v73, v92, s[38:39] offset:1024
	global_load_dword v74, v92, s[38:39] offset:2048
	global_load_dword v75, v92, s[38:39] offset:3072
	v_readlane_b32 s16, v254, 29
	s_lshl_b64 s[36:37], s[36:37], 2
	v_readlane_b32 s18, v254, 31
	v_readlane_b32 s19, v254, 32
	s_add_u32 s36, s18, s36
	s_addc_u32 s37, s19, s37
	global_load_dword v37, v173, s[36:37]
	s_movk_i32 s13, 0x900
	v_lshl_or_b32 v34, v64, 2, v63
	v_mov_b32_e32 v35, 0x100
	v_mad_u32_u24 v172, v62, s13, v35
	v_mov_b32_e32 v35, 0
	v_lshl_add_u64 v[94:95], v[34:35], 1, v[32:33]
	global_load_dwordx2 v[76:77], v[94:95], off
	global_load_dwordx2 v[78:79], v[94:95], off offset:32
	global_load_dwordx2 v[80:81], v[94:95], off offset:64
	global_load_dwordx2 v[82:83], v[94:95], off offset:96
	global_load_dwordx2 v[84:85], v[94:95], off offset:128
	global_load_dwordx2 v[86:87], v[94:95], off offset:160
	global_load_dwordx2 v[88:89], v[94:95], off offset:192
	global_load_dwordx2 v[90:91], v[94:95], off offset:224
	v_readlane_b32 s17, v254, 30
	s_lshl_b64 s[34:35], s[34:35], 1
	v_readlane_b32 s16, v255, 42
	v_readlane_b32 s17, v255, 43
	v_readlane_b32 s20, v254, 33
	v_readlane_b32 s21, v254, 34
	v_readlane_b32 s24, v254, 37
	v_readlane_b32 s18, v254, 10
	s_mov_b64 s[20:21], s[46:47]
	s_mov_b32 s24, s64
	v_readlane_b32 s22, v254, 35
	v_readlane_b32 s23, v254, 36
	v_readlane_b32 s25, v254, 38
	v_readlane_b32 s26, v254, 39
	v_readlane_b32 s27, v254, 40
	v_readlane_b32 s28, v254, 41
	v_readlane_b32 s29, v254, 42
	v_readlane_b32 s30, v254, 43
	v_readlane_b32 s31, v254, 44
	v_readlane_b32 s19, v254, 11
	s_add_u32 s38, s16, s34
	s_addc_u32 s39, s17, s35
	s_add_u32 s36, s6, s34
	s_addc_u32 s37, s7, s35
	v_lshlrev_b32_e32 v142, 13, v62
	v_lshl_add_u32 v142, v34, 2, v142
	s_waitcnt vmcnt(0)
; DI u16 f2bf(float x) { u32 u = __float_as_uint(x); u += 0x7fffu + ((u >> 16) & 1u); return (u16)(u >> 16); }
; DI float bf2f(u16 v) { return __uint_as_float(((u32)v) << 16); }
; DI void hyena_item_lat(const Params& p, int l, int it) {
;     ...
;   float ssq = 0.f;
;   for (int t = 0; t < 32; ++t) ssq += WSP(const float, OFF_PART)[(size_t)(f * 32 + t) * 256 + c];
;   const float scale = rsqrtf(ssq + EPSF);
;   const float bias = p.in[I_HYBIAS][l * 256 + c];
;   const u16* X1C = WSP(const u16, OFF_X1C);
;   u16* YM = WSP(u16, OFF_ACT);
;   const int b = l16;
; #pragma unroll
;   for (int i = 0; i < 8; ++i)
; #pragma unroll
;     for (int r = 0; r < 4; ++r) {
;       const int t = tt0 + 16 * i + kg * 4 + r;
;       const size_t row = (size_t)b * TPB + posoff + t;
;       const float uu = bf2f(UT[((size_t)(c * 16 + b)) * TPB + posoff + t]);
;       const float x1 = bf2f(X1C[row * 256 + c]);
;       YM[row * 1024 + c] = f2bf(x1 * (scale * acc[i][r] + bias * uu));
;     }
	v_add_f32_e32 v36, 0, v38
	v_add_f32_e32 v36, v36, v39
	v_add_f32_e32 v36, v36, v40
	v_add_f32_e32 v36, v36, v41
	v_add_f32_e32 v36, v36, v42
	v_add_f32_e32 v36, v36, v43
	v_add_f32_e32 v36, v36, v44
	v_add_f32_e32 v36, v36, v45
	v_add_f32_e32 v36, v36, v46
	v_add_f32_e32 v36, v36, v47
	v_add_f32_e32 v36, v36, v48
	v_add_f32_e32 v36, v36, v49
	v_add_f32_e32 v36, v36, v50
	v_add_f32_e32 v36, v36, v51
	v_add_f32_e32 v36, v36, v52
	v_add_f32_e32 v36, v36, v53
	v_add_f32_e32 v36, v36, v54
	v_add_f32_e32 v36, v36, v55
	v_add_f32_e32 v36, v36, v56
	v_add_f32_e32 v36, v36, v57
	v_add_f32_e32 v36, v36, v58
	v_add_f32_e32 v36, v36, v65
	v_add_f32_e32 v36, v36, v66
	v_add_f32_e32 v36, v36, v67
	v_add_f32_e32 v36, v36, v68
	v_add_f32_e32 v36, v36, v69
	v_add_f32_e32 v36, v36, v70
	v_add_f32_e32 v36, v36, v71
	v_add_f32_e32 v36, v36, v72
	v_add_f32_e32 v36, v36, v73
	v_add_f32_e32 v36, v36, v74
	v_add_f32_e32 v36, v36, v75
	s_mov_b32 s13, 0x800000
	v_add_f32_e32 v36, 0x358637bd, v36
	v_cmp_gt_f32_e32 vcc, s13, v36
	v_mul_f32_e32 v35, 0x4b800000, v36
	s_movk_i32 s13, 0x900
	s_nop 0
	v_cndmask_b32_e32 v36, v36, v35, vcc
	v_rsq_f32_e32 v36, v36
	s_nop 0
	v_mul_f32_e32 v35, 0x45800000, v36
	v_cndmask_b32_e32 v36, v36, v35, vcc
	v_lshlrev_b32_e32 v92, 16, v76
	v_mul_f32_e32 v92, v37, v92
	v_fmac_f32_e32 v92, v28, v36
	v_mov_b32_e32 v28, v92
	v_and_b32_e32 v92, 0xffff0000, v76
	v_mul_f32_e32 v92, v37, v92
	v_fmac_f32_e32 v92, v29, v36
	v_mov_b32_e32 v29, v92
	v_lshlrev_b32_e32 v92, 16, v77
	v_mul_f32_e32 v92, v37, v92
	v_fmac_f32_e32 v92, v30, v36
	v_mov_b32_e32 v30, v92
	v_and_b32_e32 v92, 0xffff0000, v77
	v_mul_f32_e32 v92, v37, v92
	v_fmac_f32_e32 v92, v31, v36
	v_mov_b32_e32 v31, v92
	v_lshlrev_b32_e32 v92, 16, v78
	v_mul_f32_e32 v92, v37, v92
	v_fmac_f32_e32 v92, v24, v36
	v_mov_b32_e32 v24, v92
	v_and_b32_e32 v92, 0xffff0000, v78
	v_mul_f32_e32 v92, v37, v92
	v_fmac_f32_e32 v92, v25, v36
	v_mov_b32_e32 v25, v92
	v_lshlrev_b32_e32 v92, 16, v79
	v_mul_f32_e32 v92, v37, v92
	v_fmac_f32_e32 v92, v26, v36
	v_mov_b32_e32 v26, v92
	v_and_b32_e32 v92, 0xffff0000, v79
	v_mul_f32_e32 v92, v37, v92
	v_fmac_f32_e32 v92, v27, v36
	v_mov_b32_e32 v27, v92
	v_lshlrev_b32_e32 v92, 16, v80
	v_mul_f32_e32 v92, v37, v92
	v_fmac_f32_e32 v92, v20, v36
	v_mov_b32_e32 v20, v92
	v_and_b32_e32 v92, 0xffff0000, v80
	v_mul_f32_e32 v92, v37, v92
	v_fmac_f32_e32 v92, v21, v36
	v_mov_b32_e32 v21, v92
	v_lshlrev_b32_e32 v92, 16, v81
	v_mul_f32_e32 v92, v37, v92
	v_fmac_f32_e32 v92, v22, v36
	v_mov_b32_e32 v22, v92
	v_and_b32_e32 v92, 0xffff0000, v81
	v_mul_f32_e32 v92, v37, v92
	v_fmac_f32_e32 v92, v23, v36
	v_mov_b32_e32 v23, v92
	v_lshlrev_b32_e32 v92, 16, v82
	v_mul_f32_e32 v92, v37, v92
	v_fmac_f32_e32 v92, v16, v36
	v_mov_b32_e32 v16, v92
	v_and_b32_e32 v92, 0xffff0000, v82
	v_mul_f32_e32 v92, v37, v92
	v_fmac_f32_e32 v92, v17, v36
	v_mov_b32_e32 v17, v92
	v_lshlrev_b32_e32 v92, 16, v83
	v_mul_f32_e32 v92, v37, v92
	v_fmac_f32_e32 v92, v18, v36
	v_mov_b32_e32 v18, v92
	v_and_b32_e32 v92, 0xffff0000, v83
	v_mul_f32_e32 v92, v37, v92
	v_fmac_f32_e32 v92, v19, v36
	v_mov_b32_e32 v19, v92
	v_lshlrev_b32_e32 v92, 16, v84
	v_mul_f32_e32 v92, v37, v92
	v_fmac_f32_e32 v92, v12, v36
	v_mov_b32_e32 v12, v92
	v_and_b32_e32 v92, 0xffff0000, v84
	v_mul_f32_e32 v92, v37, v92
	v_fmac_f32_e32 v92, v13, v36
	v_mov_b32_e32 v13, v92
	v_lshlrev_b32_e32 v92, 16, v85
	v_mul_f32_e32 v92, v37, v92
	v_fmac_f32_e32 v92, v14, v36
	v_mov_b32_e32 v14, v92
	v_and_b32_e32 v92, 0xffff0000, v85
	v_mul_f32_e32 v92, v37, v92
	v_fmac_f32_e32 v92, v15, v36
	v_mov_b32_e32 v15, v92
	v_lshlrev_b32_e32 v92, 16, v86
	v_mul_f32_e32 v92, v37, v92
	v_fmac_f32_e32 v92, v8, v36
	v_mov_b32_e32 v8, v92
	v_and_b32_e32 v92, 0xffff0000, v86
	v_mul_f32_e32 v92, v37, v92
	v_fmac_f32_e32 v92, v9, v36
	v_mov_b32_e32 v9, v92
	v_lshlrev_b32_e32 v92, 16, v87
	v_mul_f32_e32 v92, v37, v92
	v_fmac_f32_e32 v92, v10, v36
	v_mov_b32_e32 v10, v92
	v_and_b32_e32 v92, 0xffff0000, v87
	v_mul_f32_e32 v92, v37, v92
	v_fmac_f32_e32 v92, v11, v36
	v_mov_b32_e32 v11, v92
	v_lshlrev_b32_e32 v92, 16, v88
	v_mul_f32_e32 v92, v37, v92
	v_fmac_f32_e32 v92, v4, v36
	v_mov_b32_e32 v4, v92
	v_and_b32_e32 v92, 0xffff0000, v88
	v_mul_f32_e32 v92, v37, v92
	v_fmac_f32_e32 v92, v5, v36
	v_mov_b32_e32 v5, v92
	v_lshlrev_b32_e32 v92, 16, v89
	v_mul_f32_e32 v92, v37, v92
	v_fmac_f32_e32 v92, v6, v36
	v_mov_b32_e32 v6, v92
	v_and_b32_e32 v92, 0xffff0000, v89
	v_mul_f32_e32 v92, v37, v92
	v_fmac_f32_e32 v92, v7, v36
	v_mov_b32_e32 v7, v92
	v_lshlrev_b32_e32 v92, 16, v90
	v_mul_f32_e32 v92, v37, v92
	v_fmac_f32_e32 v92, v0, v36
	v_mov_b32_e32 v0, v92
	v_and_b32_e32 v92, 0xffff0000, v90
	v_mul_f32_e32 v92, v37, v92
	v_fmac_f32_e32 v92, v1, v36
	v_mov_b32_e32 v1, v92
	v_lshlrev_b32_e32 v92, 16, v91
	v_mul_f32_e32 v92, v37, v92
	v_fmac_f32_e32 v92, v2, v36
	v_mov_b32_e32 v2, v92
	v_and_b32_e32 v92, 0xffff0000, v91
	v_mul_f32_e32 v92, v37, v92
	v_fmac_f32_e32 v92, v3, v36
	v_mov_b32_e32 v3, v92
	s_lshl_b32 s38, s34, 16
	s_add_u32 s38, s96, s38
	s_addc_u32 s39, s97, 0
	global_store_dwordx4 v142, v[28:31], s[38:39]
	global_store_dwordx4 v142, v[24:27], s[38:39] offset:64
	global_store_dwordx4 v142, v[20:23], s[38:39] offset:128
	global_store_dwordx4 v142, v[16:19], s[38:39] offset:192
	global_store_dwordx4 v142, v[12:15], s[38:39] offset:256
	global_store_dwordx4 v142, v[8:11], s[38:39] offset:320
	global_store_dwordx4 v142, v[4:7], s[38:39] offset:384
	global_store_dwordx4 v142, v[0:3], s[38:39] offset:448
